# NSA selected-branch tile loop: PV MFMAs accumulate in place (removed 48-64 accumulator copy moves per tile), kept MFMA-to-VALU distance with s_nop
# speedup vs baseline: 1.0347x; 1.0211x over previous
; __device__ __forceinline__ void tile_soft_far(LAS const unsigned char* ks, LAS const unsigned char* vs, const bf16x8 (&qf)[4], f32x16 (&ot)[2], float& lsum, bool lane_valid, LAS const float* bt, int r, int h) {
;     const float init = lane_valid ? bt[BT_FAR] : -3.0e38f;
;     const int pr = (r & 0x13) | ((r & 4) << 1) | ((r & 8) >> 1);
;     LAS const unsigned char* kp = ks + pr * 144 + h * 16; LAS const unsigned char* vp = vs + r * 144 + h * 16;
;     bf16x8 k0[4], k1[4], v0[2][2], v1[2][2];
; #pragma unroll
;     for (int kk = 0; kk < 4; ++kk) { k0[kk] = *(LAS const bf16x8*)(kp + kk * 32); k1[kk] = *(LAS const bf16x8*)(kp + 32 * 144 + kk * 32); }
;     __builtin_amdgcn_sched_barrier(0);
;     f32x16 s0, s1;
; #pragma unroll
;     for (int i = 0; i < 16; ++i) { s0[i] = init; s1[i] = init; }
; #pragma unroll
;     for (int kk = 0; kk < 4; ++kk) s0 = MFMA32(k0[kk], qf[kk], s0);
; #pragma unroll
;     for (int mt = 0; mt < 2; ++mt)
; #pragma unroll
;         for (int j = 0; j < 2; ++j) { v0[mt][j] = *(LAS const bf16x8*)(vp + 32 * mt * 144 + 32 * j); v1[mt][j] = *(LAS const bf16x8*)(vp + 32 * mt * 144 + 64 + 32 * j); }
;     __builtin_amdgcn_sched_barrier(0);
;     s1 = MFMA32(k1[0], qf[0], s1); SOFT4(s0, 0);  __builtin_amdgcn_sched_barrier(0);
;     s1 = MFMA32(k1[1], qf[1], s1); SOFT4(s0, 4);  __builtin_amdgcn_sched_barrier(0);
;     s1 = MFMA32(k1[2], qf[2], s1); SOFT4(s0, 8);  __builtin_amdgcn_sched_barrier(0);
;     s1 = MFMA32(k1[3], qf[3], s1); SOFT4(s0, 12); __builtin_amdgcn_sched_barrier(0);
;     const bf16x8 pa = pack_p(s0, 0);
;     ot[0] = MFMA32(v0[0][0], pa, ot[0]); SOFT4(s1, 0);  __builtin_amdgcn_sched_barrier(0);
; __device__ __forceinline__ void nsa_unit(LAS unsigned char* lds, const unsigned char* hb, const bf16_t* kc, const bf16_t* vct, const float* nsg, bf16_t* omix, int b, int g, int c, int tid) {
;     ...
;         TILE_LOOP(Ks, Vs, SEQ, 0, c + 1, {
;             const int m = key0 >> 6; const unsigned sw = m < 32 ? sel0 : (m < 64 ? sel1 : (m < 96 ? sel2 : sel3));
;             const bool lane_valid = ((sw >> (m & 31)) & 1u) != 0u;
;             if (__ballot(lane_valid) != 0ull) { const int dist00 = t - (key0 + 8 * h);
;                 if ((c - m) < 3) tile_soft<1>(ks, vs, qf, ot, lsum, lane_valid, dist00, 0, bt, r, h);
;                 else tile_soft<0>(ks, vs, qf, ot, lsum, lane_valid, dist00, 0, bt, r, h); } });
.LBB0_1020:
	s_and_b32 s16, s15, 1
	s_cmpk_lt_u32 s13, 0x800
	s_cselect_b64 vcc, -1, 0
	s_cmpk_lt_u32 s13, 0x1000
	s_cselect_b64 s[6:7], -1, 0
	s_cmpk_lt_u32 s13, 0x1800
	s_cselect_b64 s[8:9], -1, 0
	v_cndmask_b32_e64 v32, v101, v100, s[8:9]
	v_cndmask_b32_e64 v32, v32, v99, s[6:7]
	v_cndmask_b32_e32 v32, v32, v98, vcc
	s_and_b32 s8, s15, 31
	v_lshrrev_b32_e32 v33, s15, v32
	v_and_b32_e32 v33, 1, v33
	v_bfe_u32 v32, v32, s8, 1
	v_cmp_eq_u32_e64 s[6:7], 1, v33
	v_cmp_ne_u32_e32 vcc, 0, v32
	s_cbranch_vccz .LBB0_1028
	s_mul_i32 s8, s16, 0x4800
	s_add_i32 s17, s8, 0x100
	s_cmp_le_i32 s15, s11
	s_mov_b64 s[8:9], -1
	s_cbranch_scc0 .LBB0_1025
	v_mov_b32_e32 v64, 0xff61b1e6
	s_and_saveexec_b64 s[8:9], s[6:7]
	ds_read_b32 v64, v211 offset:42620
	s_or_b64 exec, exec, s[8:9]
	v_add3_u32 v32, s17, v212, v154
	ds_read_b128 v[48:51], v32
	ds_read_b128 v[52:55], v32 offset:32
	ds_read_b128 v[56:59], v32 offset:4608
	ds_read_b128 v[60:63], v32 offset:4640
	ds_read_b128 v[118:121], v32 offset:64
	ds_read_b128 v[160:163], v32 offset:96
	ds_read_b128 v[170:173], v32 offset:4672
	ds_read_b128 v[174:177], v32 offset:4704
	s_waitcnt lgkmcnt(8)
	v_mov_b32_e32 v65, v64
	v_mov_b32_e32 v66, v64
	v_mov_b32_e32 v67, v64
	v_mov_b32_e32 v68, v64
	v_mov_b32_e32 v69, v64
	v_mov_b32_e32 v70, v64
	v_mov_b32_e32 v71, v64
	v_mov_b32_e32 v72, v64
	v_mov_b32_e32 v73, v64
	v_mov_b32_e32 v74, v64
	v_mov_b32_e32 v75, v64
	v_mov_b32_e32 v76, v64
	v_mov_b32_e32 v77, v64
	v_mov_b32_e32 v78, v64
	v_mov_b32_e32 v79, v64
	s_waitcnt lgkmcnt(7)
	s_nop 0
	v_mfma_f32_32x32x16_bf16 v[32:47], v[48:51], v[82:85], v[64:79]
	v_add3_u32 v48, s17, v213, v154
	s_waitcnt lgkmcnt(6)
	v_mfma_f32_32x32x16_bf16 v[32:47], v[52:55], v[86:89], v[32:47]
	s_waitcnt lgkmcnt(3)
	v_mfma_f32_32x32x16_bf16 v[32:47], v[118:121], v[90:93], v[32:47]
	ds_read_b128 v[218:221], v48 offset:9216
	ds_read_b128 v[222:225], v48 offset:9248
	ds_read_b128 v[126:129], v48 offset:9280
	ds_read_b128 v[122:125], v48 offset:9312
	ds_read_b128 v[226:229], v48 offset:13824
	ds_read_b128 v[230:233], v48 offset:13856
	ds_read_b128 v[130:133], v48 offset:13888
	ds_read_b128 v[118:121], v48 offset:13920
	s_waitcnt lgkmcnt(10)
	v_mfma_f32_32x32x16_bf16 v[32:47], v[160:163], v[94:97], v[32:47]
	s_nop 11
	v_exp_f32_e32 v32, v32
	v_exp_f32_e32 v33, v33
	v_exp_f32_e32 v34, v34
	v_exp_f32_e32 v35, v35
	v_add_f32_e32 v48, v137, v32
	v_add_f32_e32 v48, v33, v48
	v_add_f32_e32 v48, v34, v48
	v_add_f32_e32 v48, v35, v48
	v_exp_f32_e32 v36, v36
	v_exp_f32_e32 v37, v37
	v_exp_f32_e32 v38, v38
	v_exp_f32_e32 v39, v39
	v_add_f32_e32 v48, v36, v48
	v_add_f32_e32 v48, v37, v48
	v_add_f32_e32 v48, v38, v48
	v_add_f32_e32 v48, v39, v48
	v_mfma_f32_32x32x16_bf16 v[64:79], v[56:59], v[82:85], v[64:79]
	v_exp_f32_e32 v178, v40
	v_exp_f32_e32 v179, v41
	v_exp_f32_e32 v180, v42
	v_exp_f32_e32 v181, v43
	v_add_f32_e32 v40, v178, v48
	v_add_f32_e32 v40, v179, v40
	v_add_f32_e32 v40, v180, v40
	v_add_f32_e32 v40, v181, v40
	v_mfma_f32_32x32x16_bf16 v[64:79], v[60:63], v[86:89], v[64:79]
	v_exp_f32_e32 v182, v44
	s_waitcnt lgkmcnt(9)
	v_mfma_f32_32x32x16_bf16 v[64:79], v[170:173], v[90:93], v[64:79]
	v_exp_f32_e32 v170, v45
	v_exp_f32_e32 v171, v46
	v_exp_f32_e32 v172, v47
	v_add_f32_e32 v40, v182, v40
	v_add_f32_e32 v40, v170, v40
	v_add_f32_e32 v40, v171, v40
	v_add_f32_e32 v40, v172, v40
	s_waitcnt lgkmcnt(8)
	v_mfma_f32_32x32x16_bf16 v[64:79], v[174:177], v[94:97], v[64:79]
	v_cvt_pk_bf16_f32 v160, v32, v33
	v_cvt_pk_bf16_f32 v161, v34, v35
	v_cvt_pk_bf16_f32 v162, v36, v37
	v_cvt_pk_bf16_f32 v163, v38, v39
	s_nop 7
	v_exp_f32_e32 v173, v64
	v_exp_f32_e32 v174, v65
	s_waitcnt lgkmcnt(7)
	v_mfma_f32_32x32x16_bf16 v[16:31], v[218:221], v[160:163], v[16:31]
	v_exp_f32_e32 v175, v66
	v_exp_f32_e32 v176, v67
	v_add_f32_e32 v32, v173, v40
	v_add_f32_e32 v32, v174, v32
	v_add_f32_e32 v32, v175, v32
	v_add_f32_e32 v64, v176, v32
	v_exp_f32_e32 v68, v68
	v_exp_f32_e32 v69, v69
	s_waitcnt lgkmcnt(3)
	v_mfma_f32_32x32x16_bf16 v[0:15], v[226:229], v[160:163], v[0:15]
	v_exp_f32_e32 v70, v70
	v_exp_f32_e32 v71, v71
	v_add_f32_e32 v64, v68, v64
	v_add_f32_e32 v64, v69, v64
	v_add_f32_e32 v64, v70, v64
	v_add_f32_e32 v160, v71, v64
	v_cvt_pk_bf16_f32 v64, v178, v179
	v_cvt_pk_bf16_f32 v65, v180, v181
	v_cvt_pk_bf16_f32 v66, v182, v170
	v_cvt_pk_bf16_f32 v67, v171, v172
	s_nop 1
	v_mfma_f32_32x32x16_bf16 v[16:31], v[222:225], v[64:67], v[16:31]
	v_exp_f32_e32 v72, v72
	v_exp_f32_e32 v73, v73
	v_exp_f32_e32 v74, v74
	v_exp_f32_e32 v75, v75
	v_add_f32_e32 v160, v72, v160
	v_add_f32_e32 v160, v73, v160
	v_add_f32_e32 v160, v74, v160
	v_add_f32_e32 v160, v75, v160
	s_waitcnt lgkmcnt(2)
	v_mfma_f32_32x32x16_bf16 v[0:15], v[230:233], v[64:67], v[0:15]
	v_exp_f32_e32 v76, v76
	v_exp_f32_e32 v77, v77
	v_exp_f32_e32 v78, v78
	v_exp_f32_e32 v79, v79
	v_add_f32_e32 v64, v76, v160
	v_add_f32_e32 v64, v77, v64
	v_add_f32_e32 v64, v78, v64
	v_add_f32_e32 v160, v79, v64
	v_cvt_pk_bf16_f32 v64, v173, v174
	v_cvt_pk_bf16_f32 v65, v175, v176
	v_cvt_pk_bf16_f32 v66, v68, v69
	v_cvt_pk_bf16_f32 v67, v70, v71
	s_mov_b64 s[8:9], 0
	s_nop 0
	v_mfma_f32_32x32x16_bf16 v[16:31], v[126:129], v[64:67], v[16:31]
	s_waitcnt lgkmcnt(1)
	v_mfma_f32_32x32x16_bf16 v[0:15], v[130:133], v[64:67], v[0:15]
	v_cvt_pk_bf16_f32 v64, v72, v73
	v_cvt_pk_bf16_f32 v65, v74, v75
	v_cvt_pk_bf16_f32 v66, v76, v77
	v_cvt_pk_bf16_f32 v67, v78, v79
	s_nop 1
	v_mfma_f32_32x32x16_bf16 v[16:31], v[122:125], v[64:67], v[16:31]
	s_waitcnt lgkmcnt(0)
	v_mfma_f32_32x32x16_bf16 v[0:15], v[118:121], v[64:67], v[0:15]
; #define LAS __attribute__((address_space(3)))
; template <int MODE> __device__ __forceinline__ void soft_sub(f32x16& st, float& lsum, bool lane_valid, int dist0, int dmax, LAS const float* bt) {
;     ...
;     } else if (MODE == 1) {
;         float bb[16];
; #pragma unroll
;         for (int j = 0; j < 2; ++j) { int db = dist0 - 16 * j; db = db < -57 ? -57 : (db > 223 ? 223 : db); if (!lane_valid) db = -57;
;             LAS const float* p = bt + (db + 64);
; #pragma unroll
;             for (int k = 0; k < 8; ++k) bb[8 * j + k] = p[-k]; }
; #pragma unroll
;         for (int i = 0; i < 16; ++i) { const float p = ex2(st[i] + bb[i]); lsum += p; st[i] = p; }
; template <int MODE> __device__ __forceinline__ void tile_soft_gen(LAS const unsigned char* ks, LAS const unsigned char* vs, const bf16x8 (&qf)[4], f32x16 (&ot)[2], float& lsum, ...
;     const float init = MODE == 0 ? (lane_valid ? bt[BT_FAR] : -3.0e38f) : 0.f;
;     const int pr = (r & 0x13) | ((r & 4) << 1) | ((r & 8) >> 1);
;     LAS const unsigned char* kp = ks + pr * 144 + h * 16; LAS const unsigned char* vp = vs + r * 144 + h * 16;
;     bf16x8 k0[4], k1[4], v0[2][2], v1[2][2];
; #pragma unroll
;     for (int kk = 0; kk < 4; ++kk) { k0[kk] = *(LAS const bf16x8*)(kp + kk * 32); k1[kk] = *(LAS const bf16x8*)(kp + 32 * 144 + kk * 32); }
;     __builtin_amdgcn_sched_barrier(0);
;     f32x16 s0, s1;
; #pragma unroll
;     for (int i = 0; i < 16; ++i) { s0[i] = init; s1[i] = init; }
; #pragma unroll
;     for (int kk = 0; kk < 4; ++kk) s0 = MFMA32(k0[kk], qf[kk], s0);
; #pragma unroll
;     for (int mt = 0; mt < 2; ++mt)
; #pragma unroll
;         for (int j = 0; j < 2; ++j) v0[mt][j] = *(LAS const bf16x8*)(vp + 32 * mt * 144 + 32 * j);
;     __builtin_amdgcn_sched_barrier(0);
; #pragma unroll
;     for (int kk = 0; kk < 4; ++kk) s1 = MFMA32(k1[kk], qf[kk], s1);
; #pragma unroll
;     for (int mt = 0; mt < 2; ++mt)
; #pragma unroll
;         for (int j = 0; j < 2; ++j) v1[mt][j] = *(LAS const bf16x8*)(vp + 32 * mt * 144 + 64 + 32 * j);
;     soft_sub<MODE>(s0, lsum, lane_valid, dist00, dmax, bt);
;     __builtin_amdgcn_sched_barrier(0);
; #pragma unroll
;     for (int j = 0; j < 2; ++j) { const bf16x8 pf = pack_p(s0, j); ot[0] = MFMA32(v0[0][j], pf, ot[0]); ot[1] = MFMA32(v0[1][j], pf, ot[1]); }
;     soft_sub<MODE>(s1, lsum, lane_valid, dist00 - (MODE == 3 ? 512 : 32), dmax, bt);
.LBB0_1025:
	s_and_b64 vcc, exec, s[8:9]
	s_cbranch_vccz .LBB0_1027
	v_add3_u32 v48, s17, v212, v154
	s_nop 0
	ds_read_b128 v[32:35], v48
	ds_read_b128 v[36:39], v48 offset:32
	ds_read_b128 v[40:43], v48 offset:4608
	ds_read_b128 v[64:67], v48 offset:4640
	ds_read_b128 v[44:47], v48 offset:64
	ds_read_b128 v[160:163], v48 offset:96
	ds_read_b128 v[68:71], v48 offset:4672
	ds_read_b128 v[72:75], v48 offset:4704
	v_add_u32_e32 v174, 32, v135
	s_waitcnt lgkmcnt(7)
	v_mfma_f32_32x32x16_bf16 v[48:63], v[32:35], v[82:85], 0
	v_add3_u32 v170, s17, v213, v154
	ds_read_b128 v[126:129], v170 offset:9216
	ds_read_b128 v[118:121], v170 offset:9248
	ds_read_b128 v[130:133], v170 offset:13824
	ds_read_b128 v[122:125], v170 offset:13856
	s_waitcnt lgkmcnt(10)
	v_mfma_f32_32x32x16_bf16 v[48:63], v[36:39], v[86:89], v[48:63]
	s_waitcnt lgkmcnt(7)
	v_mfma_f32_32x32x16_bf16 v[48:63], v[44:47], v[90:93], v[48:63]
	v_mfma_f32_32x32x16_bf16 v[32:47], v[40:43], v[82:85], 0
	v_mfma_f32_32x32x16_bf16 v[32:47], v[64:67], v[86:89], v[32:47]
	s_waitcnt lgkmcnt(5)
	v_mfma_f32_32x32x16_bf16 v[32:47], v[68:71], v[90:93], v[32:47]
	v_mfma_f32_32x32x16_bf16 v[48:63], v[160:163], v[94:97], v[48:63]
	v_med3_i32 v160, v174, s67, v192
	v_add_u32_e32 v160, 64, v160
	v_cndmask_b32_e64 v160, 7, v160, s[6:7]
	v_lshl_add_u32 v172, v160, 2, v211
	v_add_u32_e32 v160, 0xa1fc, v172
	v_add_u32_e32 v162, 0xa1f4, v172
	v_med3_i32 v174, v174, s68, v193
	s_waitcnt lgkmcnt(4)
	v_mfma_f32_32x32x16_bf16 v[32:47], v[72:75], v[94:97], v[32:47]
	ds_read_b128 v[76:79], v170 offset:9280
	ds_read_b128 v[68:71], v170 offset:9312
	ds_read_b128 v[72:75], v170 offset:13888
	ds_read_b128 v[64:67], v170 offset:13920
	ds_read2_b32 v[160:161], v160 offset1:1
	ds_read2_b32 v[162:163], v162 offset1:1
	v_add_u32_e32 v170, 0xa1ec, v172
	ds_read2_b32 v[170:171], v170 offset1:1
	v_add_u32_e32 v172, 0xa1e4, v172
	v_add_u32_e32 v174, 48, v174
	ds_read2_b32 v[172:173], v172 offset1:1
	v_cndmask_b32_e64 v174, 7, v174, s[6:7]
	s_waitcnt lgkmcnt(3)
	v_add_f32_e32 v48, v48, v161
	v_lshl_add_u32 v180, v174, 2, v211
	v_exp_f32_e32 v48, v48
	v_add_f32_e32 v49, v49, v160
	v_add_u32_e32 v174, 0xa1fc, v180
	v_exp_f32_e32 v49, v49
	s_waitcnt lgkmcnt(2)
	v_add_f32_e32 v50, v50, v163
	ds_read2_b32 v[174:175], v174 offset1:1
	v_exp_f32_e32 v50, v50
	v_add_f32_e32 v51, v51, v162
	v_add_u32_e32 v176, 0xa1f4, v180
	v_exp_f32_e32 v51, v51
	s_waitcnt lgkmcnt(2)
	v_add_f32_e32 v52, v52, v171
	ds_read2_b32 v[176:177], v176 offset1:1
	v_add_f32_e32 v137, v137, v48
	v_exp_f32_e32 v52, v52
	v_add_f32_e32 v53, v53, v170
	v_add_u32_e32 v178, 0xa1ec, v180
	v_add_f32_e32 v137, v49, v137
	v_exp_f32_e32 v53, v53
	s_waitcnt lgkmcnt(2)
	v_add_f32_e32 v54, v54, v173
	ds_read2_b32 v[178:179], v178 offset1:1
	v_add_u32_e32 v180, 0xa1e4, v180
	v_add_f32_e32 v137, v50, v137
	v_exp_f32_e32 v54, v54
	v_add_f32_e32 v55, v55, v172
	ds_read2_b32 v[180:181], v180 offset1:1
	v_add_f32_e32 v137, v51, v137
	v_exp_f32_e32 v55, v55
	s_waitcnt lgkmcnt(3)
	v_add_f32_e32 v56, v56, v175
	v_add_f32_e32 v137, v52, v137
	v_exp_f32_e32 v56, v56
	v_add_f32_e32 v57, v57, v174
	v_add_f32_e32 v137, v53, v137
	v_exp_f32_e32 v57, v57
	s_waitcnt lgkmcnt(2)
	v_add_f32_e32 v58, v58, v177
	v_add_f32_e32 v137, v54, v137
	v_exp_f32_e32 v58, v58
	v_add_f32_e32 v59, v59, v176
	v_add_f32_e32 v137, v55, v137
	v_exp_f32_e32 v59, v59
	s_waitcnt lgkmcnt(1)
	v_add_f32_e32 v60, v60, v179
	v_add_f32_e32 v137, v56, v137
	v_exp_f32_e32 v60, v60
	v_add_f32_e32 v61, v61, v178
	v_add_f32_e32 v137, v57, v137
	v_exp_f32_e32 v61, v61
	s_waitcnt lgkmcnt(0)
; #define LAS __attribute__((address_space(3)))
; __device__ __forceinline__ float ex2(float x) { return __builtin_amdgcn_exp2f(x); }
; #define MFMA32(a, b, c) __builtin_amdgcn_mfma_f32_32x32x16_bf16((a), (b), (c), 0, 0, 0)
; template <int MODE> __device__ __forceinline__ void soft_sub(f32x16& st, float& lsum, bool lane_valid, int dist0, int dmax, LAS const float* bt) {
;     ...
;     } else if (MODE == 1) {
;         float bb[16];
; #pragma unroll
;         for (int j = 0; j < 2; ++j) { int db = dist0 - 16 * j; db = db < -57 ? -57 : (db > 223 ? 223 : db); if (!lane_valid) db = -57;
;             LAS const float* p = bt + (db + 64);
; #pragma unroll
;             for (int k = 0; k < 8; ++k) bb[8 * j + k] = p[-k]; }
; #pragma unroll
;         for (int i = 0; i < 16; ++i) { const float p = ex2(st[i] + bb[i]); lsum += p; st[i] = p; }
; template <int MODE> __device__ __forceinline__ void tile_soft_gen(LAS const unsigned char* ks, LAS const unsigned char* vs, const bf16x8 (&qf)[4], f32x16 (&ot)[2], float& lsum, ...
;     ...
;     soft_sub<MODE>(s0, lsum, lane_valid, dist00, dmax, bt);
;     __builtin_amdgcn_sched_barrier(0);
; #pragma unroll
;     for (int j = 0; j < 2; ++j) { const bf16x8 pf = pack_p(s0, j); ot[0] = MFMA32(v0[0][j], pf, ot[0]); ot[1] = MFMA32(v0[1][j], pf, ot[1]); }
;     soft_sub<MODE>(s1, lsum, lane_valid, dist00 - (MODE == 3 ? 512 : 32), dmax, bt);
;     __builtin_amdgcn_sched_barrier(0);
; #pragma unroll
;     for (int j = 0; j < 2; ++j) { const bf16x8 pf = pack_p(s1, j); ot[0] = MFMA32(v1[0][j], pf, ot[0]); ot[1] = MFMA32(v1[1][j], pf, ot[1]); }
; }
	v_add_f32_e32 v62, v62, v181
	v_add_f32_e32 v137, v58, v137
	v_exp_f32_e32 v62, v62
	v_add_f32_e32 v63, v63, v180
	v_add_f32_e32 v137, v59, v137
	v_exp_f32_e32 v63, v63
	v_add_f32_e32 v137, v60, v137
	v_add_f32_e32 v137, v61, v137
	v_add_f32_e32 v137, v62, v137
	v_add_f32_e32 v137, v63, v137
	v_cvt_pk_bf16_f32 v48, v48, v49
	v_cvt_pk_bf16_f32 v49, v50, v51
	v_cvt_pk_bf16_f32 v50, v52, v53
	v_cvt_pk_bf16_f32 v51, v54, v55
	s_nop 1
	v_mfma_f32_32x32x16_bf16 v[16:31], v[126:129], v[48:51], v[16:31]
	v_mfma_f32_32x32x16_bf16 v[0:15], v[130:133], v[48:51], v[0:15]
	v_cvt_pk_bf16_f32 v48, v56, v57
	v_cvt_pk_bf16_f32 v49, v58, v59
	v_cvt_pk_bf16_f32 v50, v60, v61
	v_cvt_pk_bf16_f32 v51, v62, v63
	v_med3_i32 v56, v135, s68, v193
	v_add_u32_e32 v56, 48, v56
	v_cndmask_b32_e64 v56, 7, v56, s[6:7]
	v_mfma_f32_32x32x16_bf16 v[16:31], v[118:121], v[48:51], v[16:31]
	v_lshl_add_u32 v62, v56, 2, v211
	v_add_u32_e32 v56, 0xa1fc, v62
	ds_read2_b32 v[56:57], v56 offset1:1
	v_add_u32_e32 v58, 0xa1f4, v62
	ds_read2_b32 v[58:59], v58 offset1:1
	v_add_u32_e32 v60, 0xa1ec, v62
	ds_read2_b32 v[60:61], v60 offset1:1
	v_mfma_f32_32x32x16_bf16 v[0:15], v[122:125], v[48:51], v[0:15]
	v_med3_i32 v48, v135, s67, v192
	v_add_u32_e32 v48, 64, v48
	v_cndmask_b32_e64 v48, 7, v48, s[6:7]
	v_lshl_add_u32 v54, v48, 2, v211
	v_add_u32_e32 v48, 0xa1fc, v54
	ds_read2_b32 v[48:49], v48 offset1:1
	v_add_u32_e32 v50, 0xa1f4, v54
	ds_read2_b32 v[50:51], v50 offset1:1
	v_add_u32_e32 v52, 0xa1ec, v54
	ds_read2_b32 v[52:53], v52 offset1:1
	v_add_u32_e32 v54, 0xa1e4, v54
	ds_read2_b32 v[54:55], v54 offset1:1
	s_waitcnt lgkmcnt(3)
	v_add_f32_e32 v32, v32, v49
	v_exp_f32_e32 v32, v32
	v_add_f32_e32 v33, v33, v48
	v_exp_f32_e32 v33, v33
	s_waitcnt lgkmcnt(2)
	v_add_f32_e32 v34, v34, v51
	v_exp_f32_e32 v34, v34
	v_add_f32_e32 v35, v35, v50
	v_exp_f32_e32 v35, v35
	s_waitcnt lgkmcnt(1)
	v_add_f32_e32 v36, v36, v53
	v_add_f32_e32 v49, v137, v32
	v_exp_f32_e32 v36, v36
	v_add_f32_e32 v37, v37, v52
	v_add_f32_e32 v48, v33, v49
	v_exp_f32_e32 v37, v37
	s_waitcnt lgkmcnt(0)
	v_add_f32_e32 v38, v38, v55
	v_add_u32_e32 v62, 0xa1e4, v62
	v_add_f32_e32 v48, v34, v48
	v_exp_f32_e32 v38, v38
	v_add_f32_e32 v39, v39, v54
	ds_read2_b32 v[62:63], v62 offset1:1
	v_add_f32_e32 v48, v35, v48
	v_exp_f32_e32 v39, v39
	v_add_f32_e32 v40, v40, v57
	v_add_f32_e32 v48, v36, v48
	v_exp_f32_e32 v40, v40
	v_add_f32_e32 v41, v41, v56
	v_add_f32_e32 v48, v37, v48
	v_exp_f32_e32 v41, v41
	v_add_f32_e32 v42, v42, v59
	v_add_f32_e32 v48, v38, v48
	v_exp_f32_e32 v42, v42
	v_add_f32_e32 v43, v43, v58
	v_add_f32_e32 v48, v39, v48
	v_exp_f32_e32 v43, v43
	v_add_f32_e32 v44, v44, v61
	v_add_f32_e32 v48, v40, v48
	v_exp_f32_e32 v44, v44
	v_add_f32_e32 v45, v45, v60
	v_add_f32_e32 v48, v41, v48
	v_exp_f32_e32 v45, v45
	s_waitcnt lgkmcnt(0)
	v_add_f32_e32 v46, v46, v63
	v_add_f32_e32 v48, v42, v48
	v_exp_f32_e32 v46, v46
	v_add_f32_e32 v47, v47, v62
	v_add_f32_e32 v48, v43, v48
	v_exp_f32_e32 v47, v47
	v_add_f32_e32 v48, v44, v48
	v_add_f32_e32 v48, v45, v48
	v_add_f32_e32 v48, v46, v48
	v_add_f32_e32 v160, v47, v48
	v_cvt_pk_bf16_f32 v32, v32, v33
	v_cvt_pk_bf16_f32 v33, v34, v35
	v_cvt_pk_bf16_f32 v34, v36, v37
	v_cvt_pk_bf16_f32 v35, v38, v39
	s_nop 1
	v_mfma_f32_32x32x16_bf16 v[16:31], v[76:79], v[32:35], v[16:31]
	v_mfma_f32_32x32x16_bf16 v[0:15], v[72:75], v[32:35], v[0:15]
	v_cvt_pk_bf16_f32 v32, v40, v41
	v_cvt_pk_bf16_f32 v33, v42, v43
	v_cvt_pk_bf16_f32 v34, v44, v45
	v_cvt_pk_bf16_f32 v35, v46, v47
	s_nop 1
	v_mfma_f32_32x32x16_bf16 v[16:31], v[68:71], v[32:35], v[16:31]
	v_mfma_f32_32x32x16_bf16 v[0:15], v[64:67], v[32:35], v[0:15]
.LBB0_1027:
	v_mov_b32_e32 v137, v160
.LBB0_1028:
	s_cmp_ge_u32 s15, s14
	s_cbranch_scc1 .LBB0_1030
	s_xor_b32 s6, s16, 1
	s_mulk_i32 s6, 0x4800
	v_add_u32_e32 v32, s6, v155
	s_waitcnt vmcnt(1)
	ds_write_b128 v32, v[102:105]
	s_waitcnt vmcnt(0)
	ds_write_b128 v32, v[106:109] offset:9216
